# v19 + prep-phase main weight-transpose loop: 8 predicated dwordx4 loads per trip issued together with counted vmcnt drains (was one load in flight per wave)
# speedup vs baseline: 1.0013x; 1.0013x over previous
; #define LAS __attribute__((address_space(3)))
; __device__ __forceinline__ void transpose_item(const float* __restrict__ W, int ldw, int k0, int srccol4, const float* __restrict__ kscale,
;                                                bf16_t* __restrict__ WT, int ldt, int n0, int kdst0, LAS float* scr, int lane) {
;     const int ks = lane >> 4, n4 = (lane & 15) * 4;
; #pragma unroll 8
;     for (int i = 0; i < 16; ++i) { const int kk = 4 * i + ks;
;         f32x4 v = srccol4 >= 0 ? *(const f32x4*)(W + (size_t)(k0 + kk) * ldw + srccol4) : (f32x4){0.f, 0.f, 0.f, 0.f};
;         if (kscale) v = v * kscale[k0 + kk];
;         LAS float* d = scr + kk * 65 + n4; d[0] = v[0]; d[1] = v[1]; d[2] = v[2]; d[3] = v[3]; }
; __global__ void __launch_bounds__(512, 2) mega_fwd(Args args) {
;     ...
;                     if (r < I_IN) { const int nb = r % (NIN / 64), kb = r / (NIN / 64); const int n0 = nb * 64;
;                         transpose_item(args.in[7] + (size_t)l * DM * INC, INC, kb * 64, in_src_col(n0 + n4), nullptr, WIN + (size_t)l * NIN * DM, DM, n0, 0, scr, lane); continue; }
.LBB0_878:
	s_sext_i32_i16 s4, s4
	s_lshl_b32 s14, s4, 6
	v_or_b32_e32 v0, s14, v52
	v_mul_hi_i32_i24_e32 v1, 0xf900, v0
	v_mul_i32_i24_e32 v0, 0xf900, v0
	v_mad_i64_i32 v[0:1], s[4:5], s12, v233, v[0:1]
	v_lshlrev_b64 v[2:3], 2, v[176:177]
	v_readlane_b32 s44, v253, 61
	v_lshl_add_u64 v[0:1], v[0:1], 0, v[2:3]
	v_readlane_b32 s58, v254, 11
	v_readlane_b32 s59, v254, 12
	v_cmp_lt_i32_e32 vcc, -1, v176
	s_mov_b64 s[26:27], 0
	v_lshl_add_u64 v[6:7], s[58:59], 0, v[0:1]
	v_or_b32_e32 v0, s14, v53
	v_mul_hi_i32_i24_e32 v1, 0xf900, v0
	v_mul_i32_i24_e32 v0, 0xf900, v0
	v_mad_i64_i32 v[0:1], s[4:5], s12, v233, v[0:1]
	v_lshl_add_u64 v[0:1], v[0:1], 0, v[2:3]
	v_lshl_add_u64 v[12:13], s[58:59], 0, v[0:1]
	v_or_b32_e32 v0, s14, v54
	v_mul_hi_i32_i24_e32 v1, 0xf900, v0
	v_mul_i32_i24_e32 v0, 0xf900, v0
	v_mad_i64_i32 v[0:1], s[4:5], s12, v233, v[0:1]
	v_lshl_add_u64 v[0:1], v[0:1], 0, v[2:3]
	v_lshl_add_u64 v[14:15], s[58:59], 0, v[0:1]
	v_or_b32_e32 v0, s14, v55
	v_mul_hi_i32_i24_e32 v1, 0xf900, v0
	v_mul_i32_i24_e32 v0, 0xf900, v0
	v_mad_i64_i32 v[0:1], s[4:5], s12, v233, v[0:1]
	v_lshl_add_u64 v[0:1], v[0:1], 0, v[2:3]
	v_lshl_add_u64 v[16:17], s[58:59], 0, v[0:1]
	v_or_b32_e32 v0, s14, v56
	v_mul_hi_i32_i24_e32 v1, 0xf900, v0
	v_mul_i32_i24_e32 v0, 0xf900, v0
	v_mad_i64_i32 v[0:1], s[4:5], s12, v233, v[0:1]
	v_lshl_add_u64 v[0:1], v[0:1], 0, v[2:3]
	v_lshl_add_u64 v[18:19], s[58:59], 0, v[0:1]
	v_or_b32_e32 v0, s14, v57
	v_mul_hi_i32_i24_e32 v1, 0xf900, v0
	v_mul_i32_i24_e32 v0, 0xf900, v0
	v_mad_i64_i32 v[0:1], s[4:5], s12, v233, v[0:1]
	v_lshl_add_u64 v[0:1], v[0:1], 0, v[2:3]
	v_lshl_add_u64 v[20:21], s[58:59], 0, v[0:1]
	v_or_b32_e32 v0, s14, v58
	v_mul_hi_i32_i24_e32 v1, 0xf900, v0
	v_mul_i32_i24_e32 v0, 0xf900, v0
	v_mad_i64_i32 v[0:1], s[4:5], s12, v233, v[0:1]
	v_lshl_add_u64 v[0:1], v[0:1], 0, v[2:3]
	v_lshl_add_u64 v[22:23], s[58:59], 0, v[0:1]
	v_or_b32_e32 v0, s14, v8
	v_mul_hi_i32_i24_e32 v1, 0xf900, v0
	v_mul_i32_i24_e32 v0, 0xf900, v0
	v_mad_i64_i32 v[0:1], s[4:5], s12, v233, v[0:1]
	v_lshl_add_u64 v[0:1], v[0:1], 0, v[2:3]
	v_lshl_add_u64 v[24:25], s[58:59], 0, v[0:1]
	v_mov_b32_e32 v26, v43
	v_readlane_b32 s45, v253, 62
	v_readlane_b32 s46, v253, 63
	v_readlane_b32 s47, v254, 0
	v_readlane_b32 s48, v254, 1
	v_readlane_b32 s49, v254, 2
	v_readlane_b32 s50, v254, 3
	v_readlane_b32 s51, v254, 4
	v_readlane_b32 s52, v254, 5
	v_readlane_b32 s53, v254, 6
	v_readlane_b32 s54, v254, 7
	v_readlane_b32 s55, v254, 8
	v_readlane_b32 s56, v254, 9
	v_readlane_b32 s57, v254, 10
	v_mov_b32_e32 v68, 0
	v_mov_b32_e32 v69, 0
	v_mov_b32_e32 v70, 0
	v_mov_b32_e32 v71, 0
	v_mov_b32_e32 v72, 0
	v_mov_b32_e32 v73, 0
	v_mov_b32_e32 v74, 0
	v_mov_b32_e32 v75, 0
	v_mov_b32_e32 v76, 0
	v_mov_b32_e32 v77, 0
	v_mov_b32_e32 v78, 0
	v_mov_b32_e32 v79, 0
	v_mov_b32_e32 v80, 0
	v_mov_b32_e32 v81, 0
	v_mov_b32_e32 v82, 0
	v_mov_b32_e32 v83, 0
	v_mov_b32_e32 v84, 0
	v_mov_b32_e32 v85, 0
	v_mov_b32_e32 v86, 0
	v_mov_b32_e32 v87, 0
	v_mov_b32_e32 v88, 0
	v_mov_b32_e32 v89, 0
	v_mov_b32_e32 v90, 0
	v_mov_b32_e32 v91, 0
	v_mov_b32_e32 v92, 0
	v_mov_b32_e32 v93, 0
	v_mov_b32_e32 v94, 0
	v_mov_b32_e32 v95, 0
	v_mov_b32_e32 v96, 0
	v_mov_b32_e32 v97, 0
	v_mov_b32_e32 v98, 0
	v_mov_b32_e32 v99, 0
TRA_FILL:
	s_and_saveexec_b64 s[28:29], vcc
	v_lshl_add_u64 v[0:1], v[24:25], 0, s[26:27]
	global_load_dwordx4 v[68:71], v[0:1], off
	v_lshl_add_u64 v[2:3], v[22:23], 0, s[26:27]
	global_load_dwordx4 v[72:75], v[2:3], off
	v_lshl_add_u64 v[4:5], v[20:21], 0, s[26:27]
	global_load_dwordx4 v[76:79], v[4:5], off
	v_lshl_add_u64 v[0:1], v[18:19], 0, s[26:27]
	global_load_dwordx4 v[80:83], v[0:1], off
	v_lshl_add_u64 v[2:3], v[16:17], 0, s[26:27]
	global_load_dwordx4 v[84:87], v[2:3], off
	v_lshl_add_u64 v[4:5], v[14:15], 0, s[26:27]
	global_load_dwordx4 v[88:91], v[4:5], off
	v_lshl_add_u64 v[0:1], v[12:13], 0, s[26:27]
	global_load_dwordx4 v[92:95], v[0:1], off
	v_lshl_add_u64 v[2:3], v[6:7], 0, s[26:27]
	global_load_dwordx4 v[96:99], v[2:3], off
	s_or_b64 exec, exec, s[28:29]
	s_add_u32 s26, s26, 0x1f2000
	s_addc_u32 s27, s27, 0
	s_cmp_lg_u32 s26, 0x3e4000
	s_waitcnt vmcnt(7)
	ds_write2_b32 v26, v68, v69 offset1:1
	ds_write2_b32 v26, v70, v71 offset0:2 offset1:3
	v_add_u32_e32 v2, 0x410, v26
	v_add_u32_e32 v3, 0x418, v26
	s_waitcnt vmcnt(6)
	ds_write2_b32 v2, v72, v73 offset1:1
	ds_write2_b32 v3, v74, v75 offset1:1
	v_add_u32_e32 v4, 0x820, v26
	v_add_u32_e32 v5, 0x828, v26
	s_waitcnt vmcnt(5)
	ds_write2_b32 v4, v76, v77 offset1:1
	ds_write2_b32 v5, v78, v79 offset1:1
	v_add_u32_e32 v0, 0xc30, v26
	v_add_u32_e32 v1, 0xc38, v26
	s_waitcnt vmcnt(4)
	ds_write2_b32 v0, v80, v81 offset1:1
	ds_write2_b32 v1, v82, v83 offset1:1
	v_add_u32_e32 v2, 0x1040, v26
	v_add_u32_e32 v3, 0x1048, v26
	s_waitcnt vmcnt(3)
	ds_write2_b32 v2, v84, v85 offset1:1
	ds_write2_b32 v3, v86, v87 offset1:1
	v_add_u32_e32 v4, 0x1450, v26
	v_add_u32_e32 v5, 0x1458, v26
	s_waitcnt vmcnt(2)
	ds_write2_b32 v4, v88, v89 offset1:1
	ds_write2_b32 v5, v90, v91 offset1:1
	v_add_u32_e32 v0, 0x1860, v26
	v_add_u32_e32 v1, 0x1868, v26
	s_waitcnt vmcnt(1)
	ds_write2_b32 v0, v92, v93 offset1:1
	ds_write2_b32 v1, v94, v95 offset1:1
	v_add_u32_e32 v2, 0x1c70, v26
	v_add_u32_e32 v3, 0x1c78, v26
	s_waitcnt vmcnt(0)
	ds_write2_b32 v2, v96, v97 offset1:1
	ds_write2_b32 v3, v98, v99 offset1:1
	v_add_u32_e32 v26, 0x2080, v26
	s_cbranch_scc1 TRA_FILL
	s_branch .LBB0_813
